# final LayerNorm (phase 15): nt hint removed from the row loads
# baseline (speedup 1.0000x reference)
.LBB0_674:
	s_cmp_lt_i32 s70, 16
	s_cselect_b64 s[0:1], -1, 0
	s_cmp_gt_i32 s71, 15
	s_cselect_b64 s[2:3], -1, 0
	s_cmp_lt_i32 s94, 0x8000
	s_cselect_b64 s[4:5], -1, 0
	s_and_b64 s[0:1], s[0:1], s[4:5]
	s_and_b64 s[0:1], s[0:1], s[2:3]
	s_andn2_b64 vcc, exec, s[0:1]
	s_cbranch_vccnz .LBB0_681
	v_readlane_b32 s6, v254, 28
	v_readlane_b32 s7, v254, 29
	v_readlane_b32 s8, v254, 30
	v_readlane_b32 s9, v254, 31
	v_readlane_b32 s10, v254, 32
	v_readlane_b32 s11, v254, 33
	s_nop 4
	s_cmp_lt_i32 s94, 0x8000
	s_cbranch_scc0 .Llnf_done
	v_lshlrev_b32_e32 v0, 4, v184
	v_lshlrev_b32_e32 v1, 5, v184
	v_xor_b32_e32 v2, 1, v184
	v_lshlrev_b32_e32 v2, 2, v2
	v_xor_b32_e32 v3, 2, v184
	v_lshlrev_b32_e32 v3, 2, v3
	v_xor_b32_e32 v4, 4, v184
	v_lshlrev_b32_e32 v4, 2, v4
	v_xor_b32_e32 v5, 8, v184
	v_lshlrev_b32_e32 v5, 2, v5
	v_xor_b32_e32 v6, 16, v184
	v_lshlrev_b32_e32 v6, 2, v6
	v_xor_b32_e32 v7, 32, v184
	v_lshlrev_b32_e32 v7, 2, v7
	v_mov_b32_e32 v8, 0x3727c5ac
	global_load_dwordx4 v[16:19], v1, s[6:7]
	global_load_dwordx4 v[20:23], v1, s[6:7] offset:16
	global_load_dwordx4 v[24:27], v1, s[6:7] offset:2048
	global_load_dwordx4 v[28:31], v1, s[6:7] offset:2064
	global_load_dwordx4 v[32:35], v1, s[8:9]
	global_load_dwordx4 v[36:39], v1, s[8:9] offset:16
	global_load_dwordx4 v[40:43], v1, s[8:9] offset:2048
	global_load_dwordx4 v[44:47], v1, s[8:9] offset:2064
	s_mov_b32 s0, s94
	s_lshl_b32 s14, s46, 2
	s_mov_b32 s5, s0
	s_lshl_b32 s4, s5, 11
	s_add_u32 s2, s62, s4
	s_addc_u32 s3, s63, 0
	global_load_dwordx4 v[48:51], v0, s[2:3]
	global_load_dwordx4 v[52:55], v0, s[2:3] offset:1024
	s_mov_b32 s4, s46
	s_add_i32 s5, s0, s4
	s_cmp_lt_i32 s5, 0x8000
	s_cselect_b32 s5, s5, s0
	s_lshl_b32 s4, s5, 11
	s_add_u32 s2, s62, s4
	s_addc_u32 s3, s63, 0
	global_load_dwordx4 v[56:59], v0, s[2:3]
	global_load_dwordx4 v[60:63], v0, s[2:3] offset:1024
	s_mul_i32 s4, s46, 2
	s_add_i32 s5, s0, s4
	s_cmp_lt_i32 s5, 0x8000
	s_cselect_b32 s5, s5, s0
	s_lshl_b32 s4, s5, 11
	s_add_u32 s2, s62, s4
	s_addc_u32 s3, s63, 0
	global_load_dwordx4 v[64:67], v0, s[2:3]
	global_load_dwordx4 v[68:71], v0, s[2:3] offset:1024
	s_mul_i32 s4, s46, 3
	s_add_i32 s5, s0, s4
	s_cmp_lt_i32 s5, 0x8000
	s_cselect_b32 s5, s5, s0
	s_lshl_b32 s4, s5, 11
	s_add_u32 s2, s62, s4
	s_addc_u32 s3, s63, 0
	global_load_dwordx4 v[72:75], v0, s[2:3]
	global_load_dwordx4 v[76:79], v0, s[2:3] offset:1024
.Llnf_top:
	s_waitcnt vmcnt(0)
	v_lshlrev_b32_e32 v112, 16, v48
	v_and_b32_e32 v113, 0xffff0000, v48
	v_lshlrev_b32_e32 v128, 16, v56
	v_and_b32_e32 v129, 0xffff0000, v56
	v_lshlrev_b32_e32 v144, 16, v64
	v_and_b32_e32 v145, 0xffff0000, v64
	v_lshlrev_b32_e32 v160, 16, v72
	v_and_b32_e32 v161, 0xffff0000, v72
	v_lshlrev_b32_e32 v114, 16, v49
	v_and_b32_e32 v115, 0xffff0000, v49
	v_lshlrev_b32_e32 v130, 16, v57
	v_and_b32_e32 v131, 0xffff0000, v57
	v_lshlrev_b32_e32 v146, 16, v65
	v_and_b32_e32 v147, 0xffff0000, v65
	v_lshlrev_b32_e32 v162, 16, v73
	v_and_b32_e32 v163, 0xffff0000, v73
	v_lshlrev_b32_e32 v116, 16, v50
	v_and_b32_e32 v117, 0xffff0000, v50
	v_lshlrev_b32_e32 v132, 16, v58
	v_and_b32_e32 v133, 0xffff0000, v58
	v_lshlrev_b32_e32 v148, 16, v66
	v_and_b32_e32 v149, 0xffff0000, v66
	v_lshlrev_b32_e32 v164, 16, v74
	v_and_b32_e32 v165, 0xffff0000, v74
	v_lshlrev_b32_e32 v118, 16, v51
	v_and_b32_e32 v119, 0xffff0000, v51
	v_lshlrev_b32_e32 v134, 16, v59
	v_and_b32_e32 v135, 0xffff0000, v59
	v_lshlrev_b32_e32 v150, 16, v67
	v_and_b32_e32 v151, 0xffff0000, v67
	v_lshlrev_b32_e32 v166, 16, v75
	v_and_b32_e32 v167, 0xffff0000, v75
	v_lshlrev_b32_e32 v120, 16, v52
	v_and_b32_e32 v121, 0xffff0000, v52
	v_lshlrev_b32_e32 v136, 16, v60
	v_and_b32_e32 v137, 0xffff0000, v60
	v_lshlrev_b32_e32 v152, 16, v68
	v_and_b32_e32 v153, 0xffff0000, v68
	v_lshlrev_b32_e32 v168, 16, v76
	v_and_b32_e32 v169, 0xffff0000, v76
	v_lshlrev_b32_e32 v122, 16, v53
	v_and_b32_e32 v123, 0xffff0000, v53
	v_lshlrev_b32_e32 v138, 16, v61
	v_and_b32_e32 v139, 0xffff0000, v61
	v_lshlrev_b32_e32 v154, 16, v69
	v_and_b32_e32 v155, 0xffff0000, v69
	v_lshlrev_b32_e32 v170, 16, v77
	v_and_b32_e32 v171, 0xffff0000, v77
	v_lshlrev_b32_e32 v124, 16, v54
	v_and_b32_e32 v125, 0xffff0000, v54
	v_lshlrev_b32_e32 v140, 16, v62
	v_and_b32_e32 v141, 0xffff0000, v62
	v_lshlrev_b32_e32 v156, 16, v70
	v_and_b32_e32 v157, 0xffff0000, v70
	v_lshlrev_b32_e32 v172, 16, v78
	v_and_b32_e32 v173, 0xffff0000, v78
	v_lshlrev_b32_e32 v126, 16, v55
	v_and_b32_e32 v127, 0xffff0000, v55
	v_lshlrev_b32_e32 v142, 16, v63
	v_and_b32_e32 v143, 0xffff0000, v63
	v_lshlrev_b32_e32 v158, 16, v71
	v_and_b32_e32 v159, 0xffff0000, v71
	v_lshlrev_b32_e32 v174, 16, v79
	v_and_b32_e32 v175, 0xffff0000, v79
	v_add_f32_e32 v176, v112, v113
	v_add_f32_e32 v178, v128, v129
	v_add_f32_e32 v180, v144, v145
	v_add_f32_e32 v182, v160, v161
	v_add_f32_e32 v176, v176, v114
	v_add_f32_e32 v178, v178, v130
	v_add_f32_e32 v180, v180, v146
	v_add_f32_e32 v182, v182, v162
	v_add_f32_e32 v176, v176, v115
	v_add_f32_e32 v178, v178, v131
	v_add_f32_e32 v180, v180, v147
	v_add_f32_e32 v182, v182, v163
	v_add_f32_e32 v176, v176, v116
	v_add_f32_e32 v178, v178, v132
	v_add_f32_e32 v180, v180, v148
	v_add_f32_e32 v182, v182, v164
	v_add_f32_e32 v176, v176, v117
	v_add_f32_e32 v178, v178, v133
	v_add_f32_e32 v180, v180, v149
	v_add_f32_e32 v182, v182, v165
	v_add_f32_e32 v176, v176, v118
	v_add_f32_e32 v178, v178, v134
	v_add_f32_e32 v180, v180, v150
	v_add_f32_e32 v182, v182, v166
	v_add_f32_e32 v176, v176, v119
	v_add_f32_e32 v178, v178, v135
	v_add_f32_e32 v180, v180, v151
	v_add_f32_e32 v182, v182, v167
	v_add_f32_e32 v176, v176, v120
	v_add_f32_e32 v178, v178, v136
	v_add_f32_e32 v180, v180, v152
	v_add_f32_e32 v182, v182, v168
	v_add_f32_e32 v176, v176, v121
	v_add_f32_e32 v178, v178, v137
	v_add_f32_e32 v180, v180, v153
	v_add_f32_e32 v182, v182, v169
	v_add_f32_e32 v176, v176, v122
	v_add_f32_e32 v178, v178, v138
	v_add_f32_e32 v180, v180, v154
	v_add_f32_e32 v182, v182, v170
	v_add_f32_e32 v176, v176, v123
	v_add_f32_e32 v178, v178, v139
	v_add_f32_e32 v180, v180, v155
	v_add_f32_e32 v182, v182, v171
	v_add_f32_e32 v176, v176, v124
	v_add_f32_e32 v178, v178, v140
	v_add_f32_e32 v180, v180, v156
	v_add_f32_e32 v182, v182, v172
	v_add_f32_e32 v176, v176, v125
	v_add_f32_e32 v178, v178, v141
	v_add_f32_e32 v180, v180, v157
	v_add_f32_e32 v182, v182, v173
	v_add_f32_e32 v176, v176, v126
	v_add_f32_e32 v178, v178, v142
	v_add_f32_e32 v180, v180, v158
	v_add_f32_e32 v182, v182, v174
	v_add_f32_e32 v176, v176, v127
	v_add_f32_e32 v178, v178, v143
	v_add_f32_e32 v180, v180, v159
	v_add_f32_e32 v182, v182, v175
	s_add_i32 s1, s0, s14
	s_cmp_lt_i32 s1, 0x8000
	s_cbranch_scc0 .Llnf_np1
	s_mov_b32 s5, s1
	s_lshl_b32 s4, s5, 11
	s_add_u32 s2, s62, s4
	s_addc_u32 s3, s63, 0
	global_load_dwordx4 v[80:83], v0, s[2:3]
	global_load_dwordx4 v[84:87], v0, s[2:3] offset:1024
	s_mov_b32 s4, s46
	s_add_i32 s5, s1, s4
	s_cmp_lt_i32 s5, 0x8000
	s_cselect_b32 s5, s5, s1
	s_lshl_b32 s4, s5, 11
	s_add_u32 s2, s62, s4
	s_addc_u32 s3, s63, 0
	global_load_dwordx4 v[88:91], v0, s[2:3]
	global_load_dwordx4 v[92:95], v0, s[2:3] offset:1024
	s_mul_i32 s4, s46, 2
	s_add_i32 s5, s1, s4
	s_cmp_lt_i32 s5, 0x8000
	s_cselect_b32 s5, s5, s1
	s_lshl_b32 s4, s5, 11
	s_add_u32 s2, s62, s4
	s_addc_u32 s3, s63, 0
	global_load_dwordx4 v[96:99], v0, s[2:3]
	global_load_dwordx4 v[100:103], v0, s[2:3] offset:1024
	s_mul_i32 s4, s46, 3
	s_add_i32 s5, s1, s4
	s_cmp_lt_i32 s5, 0x8000
	s_cselect_b32 s5, s5, s1
	s_lshl_b32 s4, s5, 11
	s_add_u32 s2, s62, s4
	s_addc_u32 s3, s63, 0
	global_load_dwordx4 v[104:107], v0, s[2:3]
	global_load_dwordx4 v[108:111], v0, s[2:3] offset:1024

.Llnf_top1:
	s_waitcnt vmcnt(16)
	v_lshlrev_b32_e32 v112, 16, v80
	v_and_b32_e32 v113, 0xffff0000, v80
	v_lshlrev_b32_e32 v128, 16, v88
	v_and_b32_e32 v129, 0xffff0000, v88
	v_lshlrev_b32_e32 v144, 16, v96
	v_and_b32_e32 v145, 0xffff0000, v96
	v_lshlrev_b32_e32 v160, 16, v104
	v_and_b32_e32 v161, 0xffff0000, v104
	v_lshlrev_b32_e32 v114, 16, v81
	v_and_b32_e32 v115, 0xffff0000, v81
	v_lshlrev_b32_e32 v130, 16, v89
	v_and_b32_e32 v131, 0xffff0000, v89
	v_lshlrev_b32_e32 v146, 16, v97
	v_and_b32_e32 v147, 0xffff0000, v97
	v_lshlrev_b32_e32 v162, 16, v105
	v_and_b32_e32 v163, 0xffff0000, v105
	v_lshlrev_b32_e32 v116, 16, v82
	v_and_b32_e32 v117, 0xffff0000, v82
	v_lshlrev_b32_e32 v132, 16, v90
	v_and_b32_e32 v133, 0xffff0000, v90
	v_lshlrev_b32_e32 v148, 16, v98
	v_and_b32_e32 v149, 0xffff0000, v98
	v_lshlrev_b32_e32 v164, 16, v106
	v_and_b32_e32 v165, 0xffff0000, v106
	v_lshlrev_b32_e32 v118, 16, v83
	v_and_b32_e32 v119, 0xffff0000, v83
	v_lshlrev_b32_e32 v134, 16, v91
	v_and_b32_e32 v135, 0xffff0000, v91
	v_lshlrev_b32_e32 v150, 16, v99
	v_and_b32_e32 v151, 0xffff0000, v99
	v_lshlrev_b32_e32 v166, 16, v107
	v_and_b32_e32 v167, 0xffff0000, v107
	v_lshlrev_b32_e32 v120, 16, v84
	v_and_b32_e32 v121, 0xffff0000, v84
	v_lshlrev_b32_e32 v136, 16, v92
	v_and_b32_e32 v137, 0xffff0000, v92
	v_lshlrev_b32_e32 v152, 16, v100
	v_and_b32_e32 v153, 0xffff0000, v100
	v_lshlrev_b32_e32 v168, 16, v108
	v_and_b32_e32 v169, 0xffff0000, v108
	v_lshlrev_b32_e32 v122, 16, v85
	v_and_b32_e32 v123, 0xffff0000, v85
	v_lshlrev_b32_e32 v138, 16, v93
	v_and_b32_e32 v139, 0xffff0000, v93
	v_lshlrev_b32_e32 v154, 16, v101
	v_and_b32_e32 v155, 0xffff0000, v101
	v_lshlrev_b32_e32 v170, 16, v109
	v_and_b32_e32 v171, 0xffff0000, v109
	v_lshlrev_b32_e32 v124, 16, v86
	v_and_b32_e32 v125, 0xffff0000, v86
	v_lshlrev_b32_e32 v140, 16, v94
	v_and_b32_e32 v141, 0xffff0000, v94
	v_lshlrev_b32_e32 v156, 16, v102
	v_and_b32_e32 v157, 0xffff0000, v102
	v_lshlrev_b32_e32 v172, 16, v110
	v_and_b32_e32 v173, 0xffff0000, v110
	v_lshlrev_b32_e32 v126, 16, v87
	v_and_b32_e32 v127, 0xffff0000, v87
	v_lshlrev_b32_e32 v142, 16, v95
	v_and_b32_e32 v143, 0xffff0000, v95
	v_lshlrev_b32_e32 v158, 16, v103
	v_and_b32_e32 v159, 0xffff0000, v103
	v_lshlrev_b32_e32 v174, 16, v111
	v_and_b32_e32 v175, 0xffff0000, v111
	v_add_f32_e32 v176, v112, v113
	v_add_f32_e32 v178, v128, v129
	v_add_f32_e32 v180, v144, v145
	v_add_f32_e32 v182, v160, v161
	v_add_f32_e32 v176, v176, v114
	v_add_f32_e32 v178, v178, v130
	v_add_f32_e32 v180, v180, v146
	v_add_f32_e32 v182, v182, v162
	v_add_f32_e32 v176, v176, v115
	v_add_f32_e32 v178, v178, v131
	v_add_f32_e32 v180, v180, v147
	v_add_f32_e32 v182, v182, v163
	v_add_f32_e32 v176, v176, v116
	v_add_f32_e32 v178, v178, v132
	v_add_f32_e32 v180, v180, v148
	v_add_f32_e32 v182, v182, v164
	v_add_f32_e32 v176, v176, v117
	v_add_f32_e32 v178, v178, v133
	v_add_f32_e32 v180, v180, v149
	v_add_f32_e32 v182, v182, v165
	v_add_f32_e32 v176, v176, v118
	v_add_f32_e32 v178, v178, v134
	v_add_f32_e32 v180, v180, v150
	v_add_f32_e32 v182, v182, v166
	v_add_f32_e32 v176, v176, v119
	v_add_f32_e32 v178, v178, v135
	v_add_f32_e32 v180, v180, v151
	v_add_f32_e32 v182, v182, v167
	v_add_f32_e32 v176, v176, v120
	v_add_f32_e32 v178, v178, v136
	v_add_f32_e32 v180, v180, v152
	v_add_f32_e32 v182, v182, v168
	v_add_f32_e32 v176, v176, v121
	v_add_f32_e32 v178, v178, v137
	v_add_f32_e32 v180, v180, v153
	v_add_f32_e32 v182, v182, v169
	v_add_f32_e32 v176, v176, v122
	v_add_f32_e32 v178, v178, v138
	v_add_f32_e32 v180, v180, v154
	v_add_f32_e32 v182, v182, v170
	v_add_f32_e32 v176, v176, v123
	v_add_f32_e32 v178, v178, v139
	v_add_f32_e32 v180, v180, v155
	v_add_f32_e32 v182, v182, v171
	v_add_f32_e32 v176, v176, v124
	v_add_f32_e32 v178, v178, v140
	v_add_f32_e32 v180, v180, v156
	v_add_f32_e32 v182, v182, v172
	v_add_f32_e32 v176, v176, v125
	v_add_f32_e32 v178, v178, v141
	v_add_f32_e32 v180, v180, v157
	v_add_f32_e32 v182, v182, v173
	v_add_f32_e32 v176, v176, v126
	v_add_f32_e32 v178, v178, v142
	v_add_f32_e32 v180, v180, v158
	v_add_f32_e32 v182, v182, v174
	v_add_f32_e32 v176, v176, v127
	v_add_f32_e32 v178, v178, v143
	v_add_f32_e32 v180, v180, v159
	v_add_f32_e32 v182, v182, v175
	s_add_i32 s1, s0, s14
	s_cmp_lt_i32 s1, 0x8000
	s_cbranch_scc0 .Llnf_np2
	s_mov_b32 s5, s1
	s_lshl_b32 s4, s5, 11
	s_add_u32 s2, s62, s4
	s_addc_u32 s3, s63, 0
	global_load_dwordx4 v[48:51], v0, s[2:3]
	global_load_dwordx4 v[52:55], v0, s[2:3] offset:1024
	s_mov_b32 s4, s46
	s_add_i32 s5, s1, s4
	s_cmp_lt_i32 s5, 0x8000
	s_cselect_b32 s5, s5, s1
	s_lshl_b32 s4, s5, 11
	s_add_u32 s2, s62, s4
	s_addc_u32 s3, s63, 0
	global_load_dwordx4 v[56:59], v0, s[2:3]
	global_load_dwordx4 v[60:63], v0, s[2:3] offset:1024
	s_mul_i32 s4, s46, 2
	s_add_i32 s5, s1, s4
	s_cmp_lt_i32 s5, 0x8000
	s_cselect_b32 s5, s5, s1
	s_lshl_b32 s4, s5, 11
	s_add_u32 s2, s62, s4
	s_addc_u32 s3, s63, 0
	global_load_dwordx4 v[64:67], v0, s[2:3]
	global_load_dwordx4 v[68:71], v0, s[2:3] offset:1024
	s_mul_i32 s4, s46, 3
	s_add_i32 s5, s1, s4
	s_cmp_lt_i32 s5, 0x8000
	s_cselect_b32 s5, s5, s1
	s_lshl_b32 s4, s5, 11
	s_add_u32 s2, s62, s4
	s_addc_u32 s3, s63, 0
	global_load_dwordx4 v[72:75], v0, s[2:3]
	global_load_dwordx4 v[76:79], v0, s[2:3] offset:1024

.Llnf_ns2_3:
	s_nop 1
	s_mov_b32 s0, s1
	s_cmp_lt_i32 s0, 0x8000
	s_cbranch_scc0 .Llnf_done
	s_waitcnt vmcnt(16)
	v_lshlrev_b32_e32 v112, 16, v48
	v_and_b32_e32 v113, 0xffff0000, v48
	v_lshlrev_b32_e32 v128, 16, v56
	v_and_b32_e32 v129, 0xffff0000, v56
	v_lshlrev_b32_e32 v144, 16, v64
	v_and_b32_e32 v145, 0xffff0000, v64
	v_lshlrev_b32_e32 v160, 16, v72
	v_and_b32_e32 v161, 0xffff0000, v72
	v_lshlrev_b32_e32 v114, 16, v49
	v_and_b32_e32 v115, 0xffff0000, v49
	v_lshlrev_b32_e32 v130, 16, v57
	v_and_b32_e32 v131, 0xffff0000, v57
	v_lshlrev_b32_e32 v146, 16, v65
	v_and_b32_e32 v147, 0xffff0000, v65
	v_lshlrev_b32_e32 v162, 16, v73
	v_and_b32_e32 v163, 0xffff0000, v73
	v_lshlrev_b32_e32 v116, 16, v50
	v_and_b32_e32 v117, 0xffff0000, v50
	v_lshlrev_b32_e32 v132, 16, v58
	v_and_b32_e32 v133, 0xffff0000, v58
	v_lshlrev_b32_e32 v148, 16, v66
	v_and_b32_e32 v149, 0xffff0000, v66
	v_lshlrev_b32_e32 v164, 16, v74
	v_and_b32_e32 v165, 0xffff0000, v74
	v_lshlrev_b32_e32 v118, 16, v51
	v_and_b32_e32 v119, 0xffff0000, v51
	v_lshlrev_b32_e32 v134, 16, v59
	v_and_b32_e32 v135, 0xffff0000, v59
	v_lshlrev_b32_e32 v150, 16, v67
	v_and_b32_e32 v151, 0xffff0000, v67
	v_lshlrev_b32_e32 v166, 16, v75
	v_and_b32_e32 v167, 0xffff0000, v75
	v_lshlrev_b32_e32 v120, 16, v52
	v_and_b32_e32 v121, 0xffff0000, v52
	v_lshlrev_b32_e32 v136, 16, v60
	v_and_b32_e32 v137, 0xffff0000, v60
	v_lshlrev_b32_e32 v152, 16, v68
	v_and_b32_e32 v153, 0xffff0000, v68
	v_lshlrev_b32_e32 v168, 16, v76
	v_and_b32_e32 v169, 0xffff0000, v76
	v_lshlrev_b32_e32 v122, 16, v53
	v_and_b32_e32 v123, 0xffff0000, v53
	v_lshlrev_b32_e32 v138, 16, v61
	v_and_b32_e32 v139, 0xffff0000, v61
	v_lshlrev_b32_e32 v154, 16, v69
	v_and_b32_e32 v155, 0xffff0000, v69
	v_lshlrev_b32_e32 v170, 16, v77
	v_and_b32_e32 v171, 0xffff0000, v77
	v_lshlrev_b32_e32 v124, 16, v54
	v_and_b32_e32 v125, 0xffff0000, v54
	v_lshlrev_b32_e32 v140, 16, v62
	v_and_b32_e32 v141, 0xffff0000, v62
	v_lshlrev_b32_e32 v156, 16, v70
	v_and_b32_e32 v157, 0xffff0000, v70
	v_lshlrev_b32_e32 v172, 16, v78
	v_and_b32_e32 v173, 0xffff0000, v78
	v_lshlrev_b32_e32 v126, 16, v55
	v_and_b32_e32 v127, 0xffff0000, v55
	v_lshlrev_b32_e32 v142, 16, v63
	v_and_b32_e32 v143, 0xffff0000, v63
	v_lshlrev_b32_e32 v158, 16, v71
	v_and_b32_e32 v159, 0xffff0000, v71
	v_lshlrev_b32_e32 v174, 16, v79
	v_and_b32_e32 v175, 0xffff0000, v79
	v_add_f32_e32 v176, v112, v113
	v_add_f32_e32 v178, v128, v129
	v_add_f32_e32 v180, v144, v145
	v_add_f32_e32 v182, v160, v161
	v_add_f32_e32 v176, v176, v114
	v_add_f32_e32 v178, v178, v130
	v_add_f32_e32 v180, v180, v146
	v_add_f32_e32 v182, v182, v162
	v_add_f32_e32 v176, v176, v115
	v_add_f32_e32 v178, v178, v131
	v_add_f32_e32 v180, v180, v147
	v_add_f32_e32 v182, v182, v163
	v_add_f32_e32 v176, v176, v116
	v_add_f32_e32 v178, v178, v132
	v_add_f32_e32 v180, v180, v148
	v_add_f32_e32 v182, v182, v164
	v_add_f32_e32 v176, v176, v117
	v_add_f32_e32 v178, v178, v133
	v_add_f32_e32 v180, v180, v149
	v_add_f32_e32 v182, v182, v165
	v_add_f32_e32 v176, v176, v118
	v_add_f32_e32 v178, v178, v134
	v_add_f32_e32 v180, v180, v150
	v_add_f32_e32 v182, v182, v166
	v_add_f32_e32 v176, v176, v119
	v_add_f32_e32 v178, v178, v135
	v_add_f32_e32 v180, v180, v151
	v_add_f32_e32 v182, v182, v167
	v_add_f32_e32 v176, v176, v120
	v_add_f32_e32 v178, v178, v136
	v_add_f32_e32 v180, v180, v152
	v_add_f32_e32 v182, v182, v168
	v_add_f32_e32 v176, v176, v121
	v_add_f32_e32 v178, v178, v137
	v_add_f32_e32 v180, v180, v153
	v_add_f32_e32 v182, v182, v169
	v_add_f32_e32 v176, v176, v122
	v_add_f32_e32 v178, v178, v138
	v_add_f32_e32 v180, v180, v154
	v_add_f32_e32 v182, v182, v170
	v_add_f32_e32 v176, v176, v123
	v_add_f32_e32 v178, v178, v139
	v_add_f32_e32 v180, v180, v155
	v_add_f32_e32 v182, v182, v171
	v_add_f32_e32 v176, v176, v124
	v_add_f32_e32 v178, v178, v140
	v_add_f32_e32 v180, v180, v156
	v_add_f32_e32 v182, v182, v172
	v_add_f32_e32 v176, v176, v125
	v_add_f32_e32 v178, v178, v141
	v_add_f32_e32 v180, v180, v157
	v_add_f32_e32 v182, v182, v173
	v_add_f32_e32 v176, v176, v126
	v_add_f32_e32 v178, v178, v142
	v_add_f32_e32 v180, v180, v158
	v_add_f32_e32 v182, v182, v174
	v_add_f32_e32 v176, v176, v127
	v_add_f32_e32 v178, v178, v143
	v_add_f32_e32 v180, v180, v159
	v_add_f32_e32 v182, v182, v175
	s_add_i32 s1, s0, s14
	s_cmp_lt_i32 s1, 0x8000
	s_cbranch_scc0 .Llnf_np3
	s_mov_b32 s5, s1
	s_lshl_b32 s4, s5, 11
	s_add_u32 s2, s62, s4
	s_addc_u32 s3, s63, 0
	global_load_dwordx4 v[80:83], v0, s[2:3]
	global_load_dwordx4 v[84:87], v0, s[2:3] offset:1024
	s_mov_b32 s4, s46
	s_add_i32 s5, s1, s4
	s_cmp_lt_i32 s5, 0x8000
	s_cselect_b32 s5, s5, s1
	s_lshl_b32 s4, s5, 11
	s_add_u32 s2, s62, s4
	s_addc_u32 s3, s63, 0
	global_load_dwordx4 v[88:91], v0, s[2:3]
	global_load_dwordx4 v[92:95], v0, s[2:3] offset:1024
	s_mul_i32 s4, s46, 2
	s_add_i32 s5, s1, s4
	s_cmp_lt_i32 s5, 0x8000
	s_cselect_b32 s5, s5, s1
	s_lshl_b32 s4, s5, 11
	s_add_u32 s2, s62, s4
	s_addc_u32 s3, s63, 0
	global_load_dwordx4 v[96:99], v0, s[2:3]
	global_load_dwordx4 v[100:103], v0, s[2:3] offset:1024
	s_mul_i32 s4, s46, 3
	s_add_i32 s5, s1, s4
	s_cmp_lt_i32 s5, 0x8000
	s_cselect_b32 s5, s5, s1
	s_lshl_b32 s4, s5, 11
	s_add_u32 s2, s62, s4
	s_addc_u32 s3, s63, 0
	global_load_dwordx4 v[104:107], v0, s[2:3]
	global_load_dwordx4 v[108:111], v0, s[2:3] offset:1024
